# combo3 + attention softmax row sums: v_pk_add_f32 beside MFMAs split into scalar v_add_f32 (same order of operations), pk-forwarding nops and 2 movs dropped
# speedup vs baseline: 1.0046x; 1.0002x over previous
.LBB0_1128:
	s_waitcnt lgkmcnt(0)
	v_mfma_f32_32x32x16_bf16 v[96:111], v[64:67], v[128:131], v[80:95]
	v_exp_f32_e32 v210, v112
	v_exp_f32_e32 v212, v113
	v_exp_f32_e32 v214, v114
	v_exp_f32_e32 v216, v115
	v_exp_f32_e32 v211, v120
	v_exp_f32_e32 v213, v121
	v_exp_f32_e32 v215, v122
	v_mfma_f32_32x32x16_bf16 v[96:111], v[68:71], v[132:135], v[96:111]
	v_exp_f32_e32 v217, v123
	v_exp_f32_e32 v220, v116
	v_exp_f32_e32 v222, v117
	v_exp_f32_e32 v224, v118
	v_exp_f32_e32 v226, v119
	v_exp_f32_e32 v221, v124
	v_exp_f32_e32 v223, v125
	v_mfma_f32_32x32x16_bf16 v[96:111], v[72:75], v[136:139], v[96:111]
	v_exp_f32_e32 v225, v126
	v_exp_f32_e32 v227, v127
	v_add_f32_e32 v64, v210, v212
	v_add_f32_e32 v65, v211, v213
	v_add_f32_e32 v66, v214, v216
	v_add_f32_e32 v67, v215, v217
	v_sub_f32_e32 v219, v201, v201
	v_add_f32_e32 v64, v64, v66
	v_add_f32_e32 v65, v65, v67
	v_add_f32_e32 v66, v220, v222
	v_add_f32_e32 v67, v221, v223
	v_mfma_f32_32x32x16_bf16 v[96:111], v[76:79], v[140:143], v[96:111]
	v_add_f32_e32 v68, v224, v226
	v_add_f32_e32 v69, v225, v227
	v_cmp_neq_f32_e64 s[0:1], 0, v219
	v_add_f32_e32 v66, v66, v68
	v_add_f32_e32 v67, v67, v69
	v_add_f32_e32 v64, v64, v66
	v_add_f32_e32 v65, v65, v67
	v_add_f32_e32 v218, v64, v65
	v_cmp_nge_f32_e32 vcc, s97, v218
	s_or_b64 vcc, s[0:1], vcc
	s_cbranch_vccz .LBB0_1130
	v_max_f32_e32 v64, v113, v113
	v_max_f32_e32 v65, v112, v112
	v_max_f32_e32 v64, v65, v64
	v_max_f32_e32 v65, v115, v115
	v_max_f32_e32 v66, v114, v114
	v_max_f32_e32 v65, v66, v65
	v_max_f32_e32 v66, v119, v119
	v_max_f32_e32 v67, v118, v118
	v_max_f32_e32 v66, v67, v66
	v_max3_f32 v66, v116, v117, v66
	v_max3_f32 v64, v64, v65, v66
	v_max_f32_e32 v65, v123, v123
	v_max_f32_e32 v66, v122, v122
	v_max_f32_e32 v65, v66, v65
	v_max_f32_e32 v66, v127, v127
	v_max_f32_e32 v67, v126, v126
	v_max_f32_e32 v66, v67, v66
	v_max3_f32 v65, v120, v121, v65
	v_max3_f32 v66, v124, v125, v66
	v_max3_f32 v64, v64, v65, v66
	v_add_f32_e32 v64, v219, v64
	ds_bpermute_b32 v65, v244, v64
	s_waitcnt lgkmcnt(0)
	v_max3_f32 v67, v64, v65, 0
	v_sub_f32_e32 v64, v67, v219
	v_sub_f32_e32 v65, v112, v64
	v_exp_f32_e32 v210, v65
	v_sub_f32_e32 v65, v113, v64
	v_exp_f32_e32 v212, v65
	v_sub_f32_e32 v65, v114, v64
	v_exp_f32_e32 v214, v65
	v_sub_f32_e32 v65, v115, v64
	v_exp_f32_e32 v216, v65
	v_sub_f32_e32 v65, v116, v64
	v_exp_f32_e32 v211, v65
	v_sub_f32_e32 v65, v117, v64
	v_exp_f32_e32 v213, v65
	v_sub_f32_e32 v65, v118, v64
	v_exp_f32_e32 v215, v65
	v_sub_f32_e32 v65, v120, v64
	v_exp_f32_e32 v112, v65
	v_sub_f32_e32 v65, v121, v64
	v_exp_f32_e32 v114, v65
	v_sub_f32_e32 v65, v122, v64
	v_exp_f32_e32 v113, v65
	v_sub_f32_e32 v65, v123, v64
	v_exp_f32_e32 v115, v65
	v_sub_f32_e32 v65, v124, v64
	v_exp_f32_e32 v116, v65
	v_sub_f32_e32 v65, v125, v64
	v_exp_f32_e32 v120, v65
	v_sub_f32_e32 v65, v126, v64
	v_exp_f32_e32 v117, v65
	v_sub_f32_e32 v65, v127, v64
	v_exp_f32_e32 v121, v65
	v_sub_f32_e32 v64, v119, v64
	v_exp_f32_e64 v66, -v67
	v_exp_f32_e32 v217, v64
	v_pk_add_f32 v[64:65], v[112:113], v[114:115]
	v_pk_add_f32 v[68:69], v[116:117], v[120:121]
	v_pk_add_f32 v[64:65], v[64:65], v[64:65] op_sel:[0,1] op_sel_hi:[1,0]
	v_pk_add_f32 v[68:69], v[68:69], v[68:69] op_sel:[0,1] op_sel_hi:[1,0]
	v_mov_b32_e32 v65, v201
	v_mov_b32_e32 v69, v67
	v_mul_f32_e32 v177, v177, v66
	v_pk_add_f32 v[80:81], v[64:65], v[68:69]
	v_pk_mul_f32 v[62:63], v[62:63], v[66:67] op_sel_hi:[1,0]
	v_pk_mul_f32 v[60:61], v[60:61], v[66:67] op_sel_hi:[1,0]
	v_pk_mul_f32 v[58:59], v[58:59], v[66:67] op_sel_hi:[1,0]
	v_pk_mul_f32 v[56:57], v[56:57], v[66:67] op_sel_hi:[1,0]
	v_pk_mul_f32 v[54:55], v[54:55], v[66:67] op_sel_hi:[1,0]
	v_pk_mul_f32 v[52:53], v[52:53], v[66:67] op_sel_hi:[1,0]
	v_pk_mul_f32 v[50:51], v[50:51], v[66:67] op_sel_hi:[1,0]
	v_pk_mul_f32 v[48:49], v[48:49], v[66:67] op_sel_hi:[1,0]
	v_pk_mul_f32 v[46:47], v[46:47], v[66:67] op_sel_hi:[1,0]
	v_pk_mul_f32 v[44:45], v[44:45], v[66:67] op_sel_hi:[1,0]
	v_pk_mul_f32 v[42:43], v[42:43], v[66:67] op_sel_hi:[1,0]
	v_pk_mul_f32 v[40:41], v[40:41], v[66:67] op_sel_hi:[1,0]
	v_pk_mul_f32 v[38:39], v[38:39], v[66:67] op_sel_hi:[1,0]
	v_pk_mul_f32 v[36:37], v[36:37], v[66:67] op_sel_hi:[1,0]
	v_pk_mul_f32 v[34:35], v[34:35], v[66:67] op_sel_hi:[1,0]
	v_pk_mul_f32 v[32:33], v[32:33], v[66:67] op_sel_hi:[1,0]
	v_pk_mul_f32 v[30:31], v[30:31], v[66:67] op_sel_hi:[1,0]
	v_pk_mul_f32 v[28:29], v[28:29], v[66:67] op_sel_hi:[1,0]
	v_pk_mul_f32 v[26:27], v[26:27], v[66:67] op_sel_hi:[1,0]
	v_pk_mul_f32 v[24:25], v[24:25], v[66:67] op_sel_hi:[1,0]
	v_pk_mul_f32 v[22:23], v[22:23], v[66:67] op_sel_hi:[1,0]
	v_pk_mul_f32 v[20:21], v[20:21], v[66:67] op_sel_hi:[1,0]
	v_pk_mul_f32 v[18:19], v[18:19], v[66:67] op_sel_hi:[1,0]
	v_pk_mul_f32 v[16:17], v[16:17], v[66:67] op_sel_hi:[1,0]
	v_pk_mul_f32 v[14:15], v[14:15], v[66:67] op_sel_hi:[1,0]
	v_pk_mul_f32 v[12:13], v[12:13], v[66:67] op_sel_hi:[1,0]
	v_pk_mul_f32 v[10:11], v[10:11], v[66:67] op_sel_hi:[1,0]
	v_pk_mul_f32 v[8:9], v[8:9], v[66:67] op_sel_hi:[1,0]
	v_pk_mul_f32 v[6:7], v[6:7], v[66:67] op_sel_hi:[1,0]
	v_pk_mul_f32 v[4:5], v[4:5], v[66:67] op_sel_hi:[1,0]
	v_pk_mul_f32 v[2:3], v[2:3], v[66:67] op_sel_hi:[1,0]
	v_pk_mul_f32 v[0:1], v[0:1], v[66:67] op_sel_hi:[1,0]
	v_pk_add_f32 v[66:67], v[214:215], v[216:217]
	v_pk_add_f32 v[68:69], v[210:211], v[212:213]
	v_xor_b32_e32 v64, 0x80000000, v81
	v_pk_add_f32 v[66:67], v[68:69], v[66:67]
	v_mov_b32_e32 v65, v64
	v_pk_add_f32 v[66:67], v[66:67], v[66:67] op_sel:[0,1] op_sel_hi:[1,0]
	v_mov_b32_e32 v68, v64
	v_mov_b32_e32 v67, v201
	v_pk_add_f32 v[218:219], v[66:67], v[80:81] neg_lo:[0,1] neg_hi:[0,1]
	v_mov_b32_e32 v67, v64
	v_add_f32_e32 v218, v66, v80
	v_mov_b32_e32 v66, v64
	v_mov_b32_e32 v69, v64
	v_mov_b32_e32 v70, v64
	v_mov_b32_e32 v71, v64
	v_mov_b32_e32 v72, v64
	v_mov_b32_e32 v73, v64
	v_mov_b32_e32 v74, v64
	v_mov_b32_e32 v75, v64
	v_mov_b32_e32 v76, v64
	v_mov_b32_e32 v77, v64
	v_mov_b32_e32 v78, v64
	v_mov_b32_e32 v79, v64
	v_mov_b32_e32 v201, v81
	v_mov_b32_e32 v80, v64
	v_mov_b32_e32 v81, v64
	v_mov_b32_e32 v82, v64
	v_mov_b32_e32 v83, v64
	v_mov_b32_e32 v84, v64
	v_mov_b32_e32 v85, v64
	v_mov_b32_e32 v86, v64
	v_mov_b32_e32 v87, v64
	v_mov_b32_e32 v88, v64
	v_mov_b32_e32 v89, v64
	v_mov_b32_e32 v90, v64
	v_mov_b32_e32 v91, v64
	v_mov_b32_e32 v92, v64
	v_mov_b32_e32 v93, v64
	v_mov_b32_e32 v94, v64
	v_mov_b32_e32 v95, v64
	v_mov_b32_e32 v220, v211
	v_mov_b32_e32 v222, v213
	v_mov_b32_e32 v224, v215
	v_mov_b32_e32 v226, v217
	v_mov_b32_e32 v211, v112
	v_mov_b32_e32 v213, v114
	v_mov_b32_e32 v215, v113
	v_mov_b32_e32 v217, v115
	v_mov_b32_e32 v221, v116
	v_mov_b32_e32 v223, v120
	v_mov_b32_e32 v225, v117
	v_mov_b32_e32 v227, v121
	v_cmp_neq_f32_e64 s[0:1], 0, v219
	s_branch .LBB0_1131
.LBB0_1130:
.LBB0_1131:
	v_cvt_pk_bf16_f32 v112, v210, v212
	v_cvt_pk_bf16_f32 v113, v214, v216
	v_cvt_pk_bf16_f32 v114, v220, v222
	v_cvt_pk_bf16_f32 v115, v224, v226
	v_cvt_pk_bf16_f32 v116, v211, v213
	v_cvt_pk_bf16_f32 v117, v215, v217
	v_mfma_f32_32x32x16_bf16 v[32:47], v[144:147], v[112:115], v[32:47]
	v_cvt_pk_bf16_f32 v118, v221, v223
	v_cvt_pk_bf16_f32 v119, v225, v227
	v_exp_f32_e32 v210, v97
	v_exp_f32_e32 v212, v98
	v_exp_f32_e32 v214, v99
	v_exp_f32_e32 v211, v101
	v_exp_f32_e32 v213, v102
	v_mfma_f32_32x32x16_bf16 v[16:31], v[148:151], v[112:115], v[16:31]
	v_exp_f32_e32 v215, v103
	v_mfma_f32_32x32x16_bf16 v[48:63], v[172:175], v[112:115], v[48:63]
	v_exp_f32_e32 v174, v96
	v_exp_f32_e32 v175, v100
	v_mfma_f32_32x32x16_bf16 v[0:15], v[152:155], v[112:115], v[0:15]
	v_add_u32_e32 v112, v250, v241
	v_mfma_f32_32x32x16_bf16 v[32:47], v[160:163], v[116:119], v[32:47]
	v_exp_f32_e32 v160, v104
	v_exp_f32_e32 v162, v105
	v_exp_f32_e32 v161, v108
	v_exp_f32_e32 v163, v109
	v_mfma_f32_32x32x16_bf16 v[16:31], v[164:167], v[116:119], v[16:31]
	v_exp_f32_e32 v164, v106
	v_exp_f32_e32 v166, v107
	v_exp_f32_e32 v165, v110
	v_exp_f32_e32 v167, v111
	v_add_f32_e32 v172, v164, v166
	v_add_f32_e32 v173, v165, v167
	v_mfma_f32_32x32x16_bf16 v[48:63], v[156:159], v[116:119], v[48:63]
	ds_read_b128 v[156:159], v112 offset:16384
	ds_read_b128 v[152:155], v112 offset:20480
	ds_read_b128 v[148:151], v112 offset:24576
	ds_read_b128 v[144:147], v112 offset:28672
	v_add_u32_e32 v112, v250, v242
	v_mfma_f32_32x32x16_bf16 v[0:15], v[168:171], v[116:119], v[0:15]
	v_add_f32_e32 v168, v174, v210
	v_add_f32_e32 v169, v175, v211
	v_add_f32_e32 v170, v212, v214
	v_add_f32_e32 v171, v213, v215
	ds_read_b128 v[124:127], v112 offset:16384
	ds_read_b128 v[120:123], v112 offset:20480
	ds_read_b128 v[116:119], v112 offset:24576
	ds_read_b128 v[112:115], v112 offset:28672
	v_add_f32_e32 v168, v168, v170
	v_add_f32_e32 v169, v169, v171
	v_add_f32_e32 v170, v160, v162
	v_add_f32_e32 v171, v161, v163
	v_add_f32_e32 v168, v168, v169
	v_add_f32_e32 v170, v170, v172
	v_add_f32_e32 v171, v171, v173
	v_add_f32_e32 v170, v170, v171
	v_add_f32_e32 v169, v177, v218
	v_add_f32_e32 v168, v168, v170
	v_cmp_nge_f32_e32 vcc, s97, v168
	s_or_b64 vcc, vcc, s[0:1]
	s_cbranch_vccz .LBB0_1133
	v_max_f32_e32 v64, v97, v97
	v_max_f32_e32 v65, v96, v96
	v_max_f32_e32 v64, v65, v64
	v_max_f32_e32 v65, v99, v99
	v_max_f32_e32 v66, v98, v98
	v_max_f32_e32 v65, v66, v65
	v_max_f32_e32 v66, v103, v103
	v_max_f32_e32 v67, v102, v102
	v_max_f32_e32 v66, v67, v66
	v_max3_f32 v66, v100, v101, v66
	v_max3_f32 v64, v64, v65, v66
	v_max_f32_e32 v65, v107, v107
	v_max_f32_e32 v66, v106, v106
	v_max_f32_e32 v65, v66, v65
	v_max_f32_e32 v66, v111, v111
	v_max_f32_e32 v67, v110, v110
	v_max_f32_e32 v66, v67, v66
	v_max3_f32 v65, v104, v105, v65
	v_max3_f32 v66, v108, v109, v66
	v_max3_f32 v64, v64, v65, v66
	v_add_f32_e32 v64, v64, v219
	ds_bpermute_b32 v65, v244, v64
	s_waitcnt lgkmcnt(0)
	v_max3_f32 v64, v64, v65, 0
	v_sub_f32_e32 v67, v64, v219
	v_sub_f32_e32 v68, v96, v67
	v_exp_f32_e32 v96, v68
	v_sub_f32_e32 v68, v97, v67
	v_exp_f32_e32 v170, v68
	v_sub_f32_e32 v68, v98, v67
	v_exp_f32_e32 v98, v68
	v_sub_f32_e32 v68, v99, v67
	v_exp_f32_e32 v172, v68
	v_sub_f32_e32 v68, v100, v67
	v_exp_f32_e32 v160, v68
	v_sub_f32_e32 v68, v101, v67
	v_exp_f32_e32 v162, v68
	v_sub_f32_e32 v68, v102, v67
	v_exp_f32_e32 v164, v68
	v_sub_f32_e32 v68, v103, v67
	v_exp_f32_e32 v166, v68
	v_sub_f32_e32 v68, v104, v67
	v_exp_f32_e32 v97, v68
	v_sub_f32_e32 v68, v105, v67
	v_exp_f32_e32 v171, v68
	v_sub_f32_e32 v68, v106, v67
	v_exp_f32_e32 v99, v68
	v_sub_f32_e32 v68, v107, v67
	v_exp_f32_e32 v173, v68
	v_sub_f32_e32 v68, v108, v67
	v_exp_f32_e32 v161, v68
	v_sub_f32_e32 v68, v109, v67
	v_exp_f32_e32 v163, v68
	v_sub_f32_e32 v68, v110, v67
	v_sub_f32_e32 v67, v111, v67
	v_exp_f32_e32 v165, v68
	v_exp_f32_e32 v167, v67
	v_exp_f32_e64 v66, -v64
	v_pk_add_f32 v[68:69], v[160:161], v[162:163]
	v_add_f32_e32 v201, v201, v64
	v_pk_add_f32 v[70:71], v[164:165], v[166:167]
	v_mul_f32_e32 v65, v169, v66
	v_pk_mul_f32 v[62:63], v[62:63], v[66:67] op_sel_hi:[1,0]
	v_pk_mul_f32 v[60:61], v[60:61], v[66:67] op_sel_hi:[1,0]
	v_pk_mul_f32 v[58:59], v[58:59], v[66:67] op_sel_hi:[1,0]
	v_pk_mul_f32 v[56:57], v[56:57], v[66:67] op_sel_hi:[1,0]
	v_pk_mul_f32 v[54:55], v[54:55], v[66:67] op_sel_hi:[1,0]
	v_pk_mul_f32 v[52:53], v[52:53], v[66:67] op_sel_hi:[1,0]
	v_pk_mul_f32 v[50:51], v[50:51], v[66:67] op_sel_hi:[1,0]
	v_pk_mul_f32 v[48:49], v[48:49], v[66:67] op_sel_hi:[1,0]
	v_pk_mul_f32 v[46:47], v[46:47], v[66:67] op_sel_hi:[1,0]
	v_pk_mul_f32 v[44:45], v[44:45], v[66:67] op_sel_hi:[1,0]
	v_pk_mul_f32 v[42:43], v[42:43], v[66:67] op_sel_hi:[1,0]
	v_pk_mul_f32 v[40:41], v[40:41], v[66:67] op_sel_hi:[1,0]
	v_pk_mul_f32 v[38:39], v[38:39], v[66:67] op_sel_hi:[1,0]
	v_pk_mul_f32 v[36:37], v[36:37], v[66:67] op_sel_hi:[1,0]
	v_pk_mul_f32 v[34:35], v[34:35], v[66:67] op_sel_hi:[1,0]
	v_pk_mul_f32 v[32:33], v[32:33], v[66:67] op_sel_hi:[1,0]
	v_pk_mul_f32 v[30:31], v[30:31], v[66:67] op_sel_hi:[1,0]
	v_pk_mul_f32 v[28:29], v[28:29], v[66:67] op_sel_hi:[1,0]
	v_pk_mul_f32 v[26:27], v[26:27], v[66:67] op_sel_hi:[1,0]
	v_pk_mul_f32 v[24:25], v[24:25], v[66:67] op_sel_hi:[1,0]
	v_pk_mul_f32 v[22:23], v[22:23], v[66:67] op_sel_hi:[1,0]
	v_pk_mul_f32 v[20:21], v[20:21], v[66:67] op_sel_hi:[1,0]
	v_pk_mul_f32 v[18:19], v[18:19], v[66:67] op_sel_hi:[1,0]
	v_pk_mul_f32 v[16:17], v[16:17], v[66:67] op_sel_hi:[1,0]
	v_pk_mul_f32 v[14:15], v[14:15], v[66:67] op_sel_hi:[1,0]
	v_pk_mul_f32 v[12:13], v[12:13], v[66:67] op_sel_hi:[1,0]
	v_pk_mul_f32 v[10:11], v[10:11], v[66:67] op_sel_hi:[1,0]
	v_pk_mul_f32 v[8:9], v[8:9], v[66:67] op_sel_hi:[1,0]
	v_pk_mul_f32 v[6:7], v[6:7], v[66:67] op_sel_hi:[1,0]
	v_pk_mul_f32 v[4:5], v[4:5], v[66:67] op_sel_hi:[1,0]
	v_pk_mul_f32 v[2:3], v[2:3], v[66:67] op_sel_hi:[1,0]
	v_pk_mul_f32 v[0:1], v[0:1], v[66:67] op_sel_hi:[1,0]
	v_pk_add_f32 v[66:67], v[98:99], v[172:173]
	v_pk_add_f32 v[68:69], v[68:69], v[70:71]
	v_pk_add_f32 v[70:71], v[96:97], v[170:171]
	v_xor_b32_e32 v64, 0x80000000, v201
	v_pk_add_f32 v[66:67], v[70:71], v[66:67]
	v_mov_b32_e32 v70, v64
	v_pk_add_f32 v[66:67], v[66:67], v[68:69]
	v_mov_b32_e32 v68, v64
	v_pk_add_f32 v[168:169], v[66:67], v[66:67] op_sel:[0,1] op_sel_hi:[1,0]
	v_mov_b32_e32 v66, v64
	v_mov_b32_e32 v169, v65
	v_mov_b32_e32 v65, v64
	v_mov_b32_e32 v67, v64
	v_mov_b32_e32 v69, v64
	v_mov_b32_e32 v71, v64
	v_mov_b32_e32 v72, v64
	v_mov_b32_e32 v73, v64
	v_mov_b32_e32 v74, v64
	v_mov_b32_e32 v75, v64
	v_mov_b32_e32 v76, v64
	v_mov_b32_e32 v77, v64
	v_mov_b32_e32 v78, v64
	v_mov_b32_e32 v79, v64
	v_mov_b32_e32 v80, v64
	v_mov_b32_e32 v81, v64
	v_mov_b32_e32 v82, v64
	v_mov_b32_e32 v83, v64
	v_mov_b32_e32 v84, v64
	v_mov_b32_e32 v85, v64
	v_mov_b32_e32 v86, v64
	v_mov_b32_e32 v87, v64
	v_mov_b32_e32 v88, v64
	v_mov_b32_e32 v89, v64
	v_mov_b32_e32 v90, v64
	v_mov_b32_e32 v91, v64
	v_mov_b32_e32 v92, v64
	v_mov_b32_e32 v93, v64
	v_mov_b32_e32 v94, v64
	v_mov_b32_e32 v95, v64
	v_mov_b32_e32 v174, v96
	v_mov_b32_e32 v210, v170
	v_mov_b32_e32 v212, v98
	v_mov_b32_e32 v214, v172
	v_mov_b32_e32 v175, v160
	v_mov_b32_e32 v211, v162
	v_mov_b32_e32 v213, v164
	v_mov_b32_e32 v215, v166
	v_mov_b32_e32 v160, v97
	v_mov_b32_e32 v162, v171
	v_mov_b32_e32 v164, v99
	v_mov_b32_e32 v166, v173
